# final phase: two rows per loop iteration (16 loads in flight per wave) when G==256; on top of v72
# speedup vs baseline: 1.0027x; 1.0027x over previous
; __device__ __forceinline__ int opaque_tid() { int t = threadIdx.x; asm volatile("" : "+v"(t)); return t; }
; __device__ __forceinline__ void final_phase(const bf16_t* xb, float* out, const float* ssq, const float* gain, int G, int wg) {
;     const int tid = opaque_tid(), lane = tid & 63, wave = tid >> 6; const int gw = wg * 8 + wave, NGW = G * 8;
;     f32x4 gv[4];
; #pragma unroll
;     for (int j = 0; j < 4; ++j) gv[j] = ((const f32x4*)gain)[lane + 64 * j];
;     for (int m = gw; m < MT; m += NGW) {
;         const float rs = __builtin_amdgcn_rsqf(pg8::ssq_row(ssq, m) * (1.f / 1024.f) + EPS);
;         const u32x2* xr = (const u32x2*)(xb + (size_t)m * DM) + lane; f32x4* orow = (f32x4*)(out + (size_t)m * DM) + lane;
.LBB0_1924:
	s_cmp_ge_i32 s86, s26
	s_cselect_b64 s[0:1], -1, 0
	s_cmp_lt_i32 s86, s27
	s_cselect_b64 s[2:3], -1, 0
	s_and_b64 s[0:1], s[0:1], s[2:3]
	s_and_b64 vcc, exec, s[0:1]
	s_cbranch_vccz .LBB0_1982
	v_readlane_b32 s4, v254, 52
	v_ashrrev_i32_e32 v16, 6, v210
	s_mov_b32 s0, 0x8000
	v_add_u32_e32 v22, s4, v16
	v_cmp_gt_i32_e32 vcc, s0, v22
	v_readlane_b32 s5, v254, 53
	s_and_saveexec_b64 s[0:1], vcc
	v_readlane_b32 s12, v253, 53
	v_readlane_b32 s13, v253, 54
	s_cbranch_execz .LBB0_1928
	v_and_b32_e32 v23, 63, v210
	s_waitcnt vmcnt(0)
	v_lshlrev_b32_e32 v24, 4, v23
	s_waitcnt lgkmcnt(0)
	global_load_dwordx4 v[0:3], v24, s[74:75]
	global_load_dwordx4 v[4:7], v24, s[74:75] offset:1024
	global_load_dwordx4 v[8:11], v24, s[74:75] offset:2048
	global_load_dwordx4 v[12:15], v24, s[74:75] offset:3072
	v_ashrrev_i32_e32 v17, 31, v16
	s_ashr_i32 s5, s4, 31
	v_lshl_add_u64 v[20:21], v[16:17], 0, s[4:5]
	v_lshlrev_b64 v[16:17], 6, v[20:21]
	v_lshlrev_b64 v[18:19], 12, v[20:21]
	v_readlane_b32 s36, v252, 16
	v_lshlrev_b64 v[20:21], 11, v[20:21]
	v_or_b32_e32 v18, v18, v24
	v_readlane_b32 s46, v252, 26
	v_readlane_b32 s47, v252, 27
	v_readlane_b32 s50, v252, 30
	v_readlane_b32 s51, v252, 31
	v_lshl_or_b32 v20, v23, 3, v20
	v_lshl_add_u64 v[16:17], s[24:25], 0, v[16:17]
	s_ashr_i32 s13, s12, 31
	v_readlane_b32 s46, v252, 46
	v_lshl_add_u64 v[18:19], s[50:51], 0, v[18:19]
	s_mov_b64 s[4:5], 0x800
	v_lshl_add_u64 v[20:21], s[24:25], 0, v[20:21]
	s_mov_b64 s[6:7], 0x6200400
	v_lshl_add_u64 v[16:17], v[16:17], 0, 32
	s_lshl_b64 s[2:3], s[12:13], 6
	v_readlane_b32 s47, v252, 47
	v_lshl_add_u64 v[18:19], v[18:19], 0, s[4:5]
	s_lshl_b64 s[4:5], s[12:13], 12
	v_lshl_add_u64 v[20:21], v[20:21], 0, s[6:7]
	s_lshl_b64 s[6:7], s[12:13], 11
	s_mov_b64 s[10:11], 0
	v_mov_b32_e32 v23, 0x358637bd
	s_movk_i32 s8, 0x7fff
	v_readlane_b32 s37, v252, 17
	v_readlane_b32 s38, v252, 18
	v_readlane_b32 s39, v252, 19
	v_readlane_b32 s40, v252, 20
	v_readlane_b32 s41, v252, 21
	v_readlane_b32 s42, v252, 22
	v_readlane_b32 s43, v252, 23
	v_readlane_b32 s44, v252, 24
	v_readlane_b32 s45, v252, 25
	v_readlane_b32 s48, v252, 28
	v_readlane_b32 s49, v252, 29
	s_cmp_eq_u32 s28, 0x100
	s_cbranch_scc1 .Lfin2_loop

; __device__ __forceinline__ void final_phase(const bf16_t* xb, float* out, const float* ssq, const float* gain, int G, int wg) {
;     ...
;     for (int m = gw; m < MT; m += NGW) {
;         const float rs = __builtin_amdgcn_rsqf(pg8::ssq_row(ssq, m) * (1.f / 1024.f) + EPS);
;         const u32x2* xr = (const u32x2*)(xb + (size_t)m * DM) + lane; f32x4* orow = (f32x4*)(out + (size_t)m * DM) + lane;
; #pragma unroll
;         for (int j = 0; j < 4; ++j) { const u32x2 w = xr[64 * j];
;             const f32x4 v = {__builtin_bit_cast(float, w.x << 16), __builtin_bit_cast(float, w.x & 0xffff0000u), __builtin_bit_cast(float, w.y << 16), __builtin_bit_cast(float, w.y & 0xffff0000u)};
;             orow[64 * j] = v * rs * gv[j]; }
;     }
.Lfin2_loop:
	v_lshl_add_u64 v[76:77], v[16:17], 0, s[2:3]
	v_lshl_add_u64 v[78:79], v[20:21], 0, s[6:7]
	v_lshl_add_u64 v[80:81], v[18:19], 0, s[4:5]
	global_load_dwordx4 v[24:27], v[16:17], off offset:-32
	global_load_dwordx4 v[28:31], v[16:17], off
	global_load_dwordx4 v[32:35], v[16:17], off offset:-16
	global_load_dwordx4 v[36:39], v[16:17], off offset:16
	global_load_dwordx2 v[40:41], v[20:21], off offset:-1024 nt
	global_load_dwordx2 v[44:45], v[20:21], off offset:-512 nt
	global_load_dwordx2 v[46:47], v[20:21], off nt
	global_load_dwordx2 v[48:49], v[20:21], off offset:512 nt
	global_load_dwordx4 v[50:53], v[76:77], off offset:-32
	global_load_dwordx4 v[54:57], v[76:77], off
	global_load_dwordx4 v[58:61], v[76:77], off offset:-16
	global_load_dwordx4 v[62:65], v[76:77], off offset:16
	global_load_dwordx2 v[66:67], v[78:79], off offset:-1024 nt
	global_load_dwordx2 v[70:71], v[78:79], off offset:-512 nt
	global_load_dwordx2 v[72:73], v[78:79], off nt
	global_load_dwordx2 v[74:75], v[78:79], off offset:512 nt
	v_add_u32_e32 v22, s12, v22
	v_add_u32_e32 v22, s12, v22
	v_cmp_lt_i32_e32 vcc, s8, v22
	v_lshl_add_u64 v[16:17], v[76:77], 0, s[2:3]
	v_lshl_add_u64 v[20:21], v[78:79], 0, s[6:7]
	s_or_b64 s[10:11], vcc, s[10:11]
	s_waitcnt vmcnt(15)
	v_mov_b32_e32 v42, v24
	s_waitcnt vmcnt(14)
	v_mov_b32_e32 v43, v28
	v_mov_b32_e32 v28, v25
	v_mov_b32_e32 v24, v26
	v_mov_b32_e32 v25, v30
	v_mov_b32_e32 v30, v27
	s_waitcnt vmcnt(13)
	v_mov_b32_e32 v26, v32
	s_waitcnt vmcnt(12)
	v_mov_b32_e32 v27, v36
	v_mov_b32_e32 v36, v33
	v_mov_b32_e32 v32, v34
	v_mov_b32_e32 v33, v38
	v_mov_b32_e32 v38, v35
	v_pk_add_f32 v[28:29], v[42:43], v[28:29]
	v_pk_add_f32 v[24:25], v[24:25], v[30:31]
	v_pk_add_f32 v[26:27], v[26:27], v[36:37]
	v_pk_add_f32 v[30:31], v[32:33], v[38:39]
	v_pk_add_f32 v[24:25], v[28:29], v[24:25]
	v_pk_add_f32 v[26:27], v[26:27], v[30:31]
	s_waitcnt vmcnt(11)
	v_lshlrev_b32_e32 v34, 16, v40
	v_pk_add_f32 v[24:25], v[24:25], v[26:27]
	v_and_b32_e32 v35, 0xffff0000, v40
	v_add_f32_e32 v24, v24, v25
	v_fmamk_f32 v24, v24, 0x3a800000, v23
	v_rsq_f32_e32 v28, v24
	v_lshlrev_b32_e32 v40, 16, v41
	v_and_b32_e32 v41, 0xffff0000, v41
	v_pk_mul_f32 v[24:25], v[28:29], v[34:35] op_sel_hi:[0,1]
	v_pk_mul_f32 v[26:27], v[28:29], v[40:41] op_sel_hi:[0,1]
	v_pk_mul_f32 v[26:27], v[2:3], v[26:27]
	v_pk_mul_f32 v[24:25], v[0:1], v[24:25]
	global_store_dwordx4 v[18:19], v[24:27], off offset:-2048 nt
	s_waitcnt vmcnt(11)
	s_nop 1
	v_lshlrev_b32_e32 v26, 16, v44
	v_and_b32_e32 v27, 0xffff0000, v44
	v_lshlrev_b32_e32 v24, 16, v45
	v_and_b32_e32 v25, 0xffff0000, v45
	v_pk_mul_f32 v[30:31], v[28:29], v[26:27] op_sel_hi:[0,1]
	v_pk_mul_f32 v[24:25], v[28:29], v[24:25] op_sel_hi:[0,1]
	v_pk_mul_f32 v[26:27], v[6:7], v[24:25]
	v_pk_mul_f32 v[24:25], v[4:5], v[30:31]
	global_store_dwordx4 v[18:19], v[24:27], off offset:-1024 nt
	s_waitcnt vmcnt(11)
	s_nop 1
	v_lshlrev_b32_e32 v26, 16, v46
	v_and_b32_e32 v27, 0xffff0000, v46
	v_lshlrev_b32_e32 v24, 16, v47
	v_and_b32_e32 v25, 0xffff0000, v47
	v_pk_mul_f32 v[30:31], v[28:29], v[26:27] op_sel_hi:[0,1]
	v_pk_mul_f32 v[24:25], v[28:29], v[24:25] op_sel_hi:[0,1]
	v_pk_mul_f32 v[26:27], v[10:11], v[24:25]
	v_pk_mul_f32 v[24:25], v[8:9], v[30:31]
	global_store_dwordx4 v[18:19], v[24:27], off nt
	s_waitcnt vmcnt(11)
	s_nop 1
	v_lshlrev_b32_e32 v26, 16, v48
	v_and_b32_e32 v27, 0xffff0000, v48
	v_lshlrev_b32_e32 v24, 16, v49
	v_and_b32_e32 v25, 0xffff0000, v49
	v_pk_mul_f32 v[30:31], v[28:29], v[26:27] op_sel_hi:[0,1]
	v_pk_mul_f32 v[24:25], v[28:29], v[24:25] op_sel_hi:[0,1]
	v_pk_mul_f32 v[26:27], v[14:15], v[24:25]
	v_pk_mul_f32 v[24:25], v[12:13], v[30:31]
	global_store_dwordx4 v[18:19], v[24:27], off offset:1024 nt
	s_waitcnt vmcnt(11)
	v_mov_b32_e32 v68, v50
	s_waitcnt vmcnt(10)
	v_mov_b32_e32 v69, v54
	v_mov_b32_e32 v54, v51
	v_mov_b32_e32 v50, v52
	v_mov_b32_e32 v51, v56
	v_mov_b32_e32 v56, v53
	s_waitcnt vmcnt(9)
	v_mov_b32_e32 v52, v58
	s_waitcnt vmcnt(8)
	v_mov_b32_e32 v53, v62
	v_mov_b32_e32 v62, v59
	v_mov_b32_e32 v58, v60
	v_mov_b32_e32 v59, v64
	v_mov_b32_e32 v64, v61
	v_pk_add_f32 v[54:55], v[68:69], v[54:55]
	v_pk_add_f32 v[50:51], v[50:51], v[56:57]
	v_pk_add_f32 v[52:53], v[52:53], v[62:63]
	v_pk_add_f32 v[56:57], v[58:59], v[64:65]
	v_pk_add_f32 v[50:51], v[54:55], v[50:51]
	v_pk_add_f32 v[52:53], v[52:53], v[56:57]
	s_waitcnt vmcnt(7)
	v_lshlrev_b32_e32 v60, 16, v66
	v_pk_add_f32 v[50:51], v[50:51], v[52:53]
	v_and_b32_e32 v61, 0xffff0000, v66
	v_add_f32_e32 v50, v50, v51
	v_fmamk_f32 v50, v50, 0x3a800000, v23
	v_rsq_f32_e32 v54, v50
	v_lshlrev_b32_e32 v66, 16, v67
	v_and_b32_e32 v67, 0xffff0000, v67
	v_pk_mul_f32 v[50:51], v[54:55], v[60:61] op_sel_hi:[0,1]
	v_pk_mul_f32 v[52:53], v[54:55], v[66:67] op_sel_hi:[0,1]
	v_pk_mul_f32 v[52:53], v[2:3], v[52:53]
	v_pk_mul_f32 v[50:51], v[0:1], v[50:51]
	global_store_dwordx4 v[80:81], v[50:53], off offset:-2048 nt
	s_waitcnt vmcnt(7)
	s_nop 1
	v_lshlrev_b32_e32 v52, 16, v70
	v_and_b32_e32 v53, 0xffff0000, v70
	v_lshlrev_b32_e32 v50, 16, v71
	v_and_b32_e32 v51, 0xffff0000, v71
	v_pk_mul_f32 v[56:57], v[54:55], v[52:53] op_sel_hi:[0,1]
	v_pk_mul_f32 v[50:51], v[54:55], v[50:51] op_sel_hi:[0,1]
	v_pk_mul_f32 v[52:53], v[6:7], v[50:51]
	v_pk_mul_f32 v[50:51], v[4:5], v[56:57]
	global_store_dwordx4 v[80:81], v[50:53], off offset:-1024 nt
	s_waitcnt vmcnt(7)
	s_nop 1
	v_lshlrev_b32_e32 v52, 16, v72
	v_and_b32_e32 v53, 0xffff0000, v72
	v_lshlrev_b32_e32 v50, 16, v73
	v_and_b32_e32 v51, 0xffff0000, v73
	v_pk_mul_f32 v[56:57], v[54:55], v[52:53] op_sel_hi:[0,1]
	v_pk_mul_f32 v[50:51], v[54:55], v[50:51] op_sel_hi:[0,1]
	v_pk_mul_f32 v[52:53], v[10:11], v[50:51]
	v_pk_mul_f32 v[50:51], v[8:9], v[56:57]
	global_store_dwordx4 v[80:81], v[50:53], off nt
	s_waitcnt vmcnt(7)
	s_nop 1
	v_lshlrev_b32_e32 v52, 16, v74
	v_and_b32_e32 v53, 0xffff0000, v74
	v_lshlrev_b32_e32 v50, 16, v75
	v_and_b32_e32 v51, 0xffff0000, v75
	v_pk_mul_f32 v[56:57], v[54:55], v[52:53] op_sel_hi:[0,1]
	v_pk_mul_f32 v[50:51], v[54:55], v[50:51] op_sel_hi:[0,1]
	v_pk_mul_f32 v[52:53], v[14:15], v[50:51]
	v_pk_mul_f32 v[50:51], v[12:13], v[56:57]
	global_store_dwordx4 v[80:81], v[50:53], off offset:1024 nt
	v_lshl_add_u64 v[18:19], v[80:81], 0, s[4:5]
	s_andn2_b64 exec, exec, s[10:11]
	s_cbranch_execnz .Lfin2_loop
	s_branch .LBB0_1928
